# XCD-local barrier: waiters poll the per-XCD arrival counter (count >= target) instead of the generation word published by the last arriver
# baseline (speedup 1.0000x reference)
.LBB0_196:
	s_or_b64 exec, exec, s[8:9]
	v_cvt_f32_u32_e32 v4, v2
	s_waitcnt vmcnt(0)
	v_readfirstlane_b32 s4, v3
	v_sub_u32_e32 v3, 0, v2
	v_rcp_iflag_f32_e32 v4, v4
	v_add_u32_e32 v5, s4, v1
	v_mul_f32_e32 v4, 0x4f7ffffe, v4
	v_cvt_u32_f32_e32 v4, v4
	v_mul_lo_u32 v1, v3, v4
	v_mul_hi_u32 v1, v4, v1
	v_add_u32_e32 v1, v4, v1
	v_mul_hi_u32 v1, v5, v1
	v_mul_lo_u32 v3, v1, v2
	v_sub_u32_e32 v3, v5, v3
	v_add_u32_e32 v4, 1, v1
	v_cmp_ge_u32_e32 vcc, v3, v2
	s_nop 1
	v_cndmask_b32_e32 v1, v1, v4, vcc
	v_sub_u32_e32 v4, v3, v2
	v_cndmask_b32_e32 v3, v3, v4, vcc
	v_add_u32_e32 v4, 1, v1
	v_cmp_ge_u32_e32 vcc, v3, v2
	v_add_u32_e32 v3, 1, v5
	s_nop 0
	v_cndmask_b32_e32 v1, v1, v4, vcc
	v_mul_lo_u32 v4, v2, v1
	v_add_u32_e32 v2, v4, v2
	v_cmp_ne_u32_e32 vcc, v3, v2
	s_and_saveexec_b64 s[4:5], vcc
	s_xor_b64 s[8:9], exec, s[4:5]
	s_cbranch_execz .LBB0_210
	s_cmp_lg_u32 s101, 0
	s_cselect_b32 s98, 26, 28
	s_cselect_b32 s99, 27, 29
	s_nop 3
	v_readlane_b32 s4, v254, s98
	v_readlane_b32 s5, v254, s99
	s_waitcnt lgkmcnt(0)
	s_nop 3
	global_load_dword v0, v177, s[4:5] sc1
	s_waitcnt vmcnt(0)
	s_cmp_lg_u32 s101, 0
	s_cbranch_scc0 .Lpc_0
	v_cmp_ge_u32_e32 vcc, v0, v2
	s_nop 1
	v_addc_co_u32_e32 v0, vcc, 0, v1, vcc
.Lpc_0:
	v_cmp_eq_u32_e32 vcc, v0, v1
	s_and_saveexec_b64 s[12:13], vcc
	s_cbranch_execz .LBB0_209
	s_mov_b32 s16, 1
	s_mov_b64 s[10:11], 0
	s_branch .LBB0_200

.LBB0_204:
	s_cmp_lg_u32 s101, 0
	s_cselect_b32 s98, 26, 28
	s_cselect_b32 s99, 27, 29
	s_nop 3
	v_readlane_b32 s4, v254, s98
	v_readlane_b32 s5, v254, s99
	s_add_i32 s16, s16, 1
	s_mov_b64 s[28:29], -1
	s_nop 2
	global_load_dword v0, v177, s[4:5] sc1
	s_waitcnt vmcnt(0)
	s_cmp_lg_u32 s101, 0
	s_cbranch_scc0 .Lpc_1
	v_cmp_ge_u32_e32 vcc, v0, v2
	s_nop 1
	v_addc_co_u32_e32 v0, vcc, 0, v1, vcc
.Lpc_1:
	v_cmp_ne_u32_e32 vcc, v0, v1
	s_orn2_b64 s[26:27], vcc, exec
	s_branch .LBB0_199

.LBB0_346:
	s_or_b64 exec, exec, s[6:7]
	v_cvt_f32_u32_e32 v4, v2
	s_waitcnt vmcnt(0)
	v_readfirstlane_b32 s4, v3
	v_sub_u32_e32 v3, 0, v2
	v_rcp_iflag_f32_e32 v4, v4
	v_add_u32_e32 v5, s4, v1
	v_mul_f32_e32 v4, 0x4f7ffffe, v4
	v_cvt_u32_f32_e32 v4, v4
	v_mul_lo_u32 v1, v3, v4
	v_mul_hi_u32 v1, v4, v1
	v_add_u32_e32 v1, v4, v1
	v_mul_hi_u32 v1, v5, v1
	v_mul_lo_u32 v3, v1, v2
	v_sub_u32_e32 v3, v5, v3
	v_add_u32_e32 v4, 1, v1
	v_cmp_ge_u32_e32 vcc, v3, v2
	s_nop 1
	v_cndmask_b32_e32 v1, v1, v4, vcc
	v_sub_u32_e32 v4, v3, v2
	v_cndmask_b32_e32 v3, v3, v4, vcc
	v_add_u32_e32 v4, 1, v1
	v_cmp_ge_u32_e32 vcc, v3, v2
	v_add_u32_e32 v3, 1, v5
	s_nop 0
	v_cndmask_b32_e32 v1, v1, v4, vcc
	v_mul_lo_u32 v4, v2, v1
	v_add_u32_e32 v2, v4, v2
	v_cmp_ne_u32_e32 vcc, v3, v2
	s_and_saveexec_b64 s[4:5], vcc
	s_xor_b64 s[6:7], exec, s[4:5]
	s_cbranch_execz .LBB0_360
	s_cmp_lg_u32 s101, 0
	s_cselect_b32 s98, 26, 28
	s_cselect_b32 s99, 27, 29
	s_nop 3
	v_readlane_b32 s4, v254, s98
	v_readlane_b32 s5, v254, s99
	s_waitcnt lgkmcnt(0)
	s_nop 3
	global_load_dword v0, v177, s[4:5] sc1
	s_waitcnt vmcnt(0)
	s_cmp_lg_u32 s101, 0
	s_cbranch_scc0 .Lpc_2
	v_cmp_ge_u32_e32 vcc, v0, v2
	s_nop 1
	v_addc_co_u32_e32 v0, vcc, 0, v1, vcc
.Lpc_2:
	v_cmp_eq_u32_e32 vcc, v0, v1
	s_and_saveexec_b64 s[8:9], vcc
	s_cbranch_execz .LBB0_359
	s_mov_b32 s16, 1
	s_mov_b64 s[10:11], 0
	s_branch .LBB0_350

.LBB0_354:
	s_cmp_lg_u32 s101, 0
	s_cselect_b32 s98, 26, 28
	s_cselect_b32 s99, 27, 29
	s_nop 3
	v_readlane_b32 s4, v254, s98
	v_readlane_b32 s5, v254, s99
	s_add_i32 s16, s16, 1
	s_mov_b64 s[20:21], -1
	s_nop 2
	global_load_dword v0, v177, s[4:5] sc1
	s_waitcnt vmcnt(0)
	s_cmp_lg_u32 s101, 0
	s_cbranch_scc0 .Lpc_3
	v_cmp_ge_u32_e32 vcc, v0, v2
	s_nop 1
	v_addc_co_u32_e32 v0, vcc, 0, v1, vcc
.Lpc_3:
	v_cmp_ne_u32_e32 vcc, v0, v1
	s_orn2_b64 s[18:19], vcc, exec
	s_branch .LBB0_349

.LBB0_745:
	s_or_b64 exec, exec, s[6:7]
	v_cvt_f32_u32_e32 v4, v2
	s_waitcnt vmcnt(0)
	v_readfirstlane_b32 s4, v3
	v_sub_u32_e32 v3, 0, v2
	v_rcp_iflag_f32_e32 v4, v4
	v_add_u32_e32 v5, s4, v1
	v_mul_f32_e32 v4, 0x4f7ffffe, v4
	v_cvt_u32_f32_e32 v4, v4
	v_mul_lo_u32 v1, v3, v4
	v_mul_hi_u32 v1, v4, v1
	v_add_u32_e32 v1, v4, v1
	v_mul_hi_u32 v1, v5, v1
	v_mul_lo_u32 v3, v1, v2
	v_sub_u32_e32 v3, v5, v3
	v_add_u32_e32 v4, 1, v1
	v_cmp_ge_u32_e32 vcc, v3, v2
	s_nop 1
	v_cndmask_b32_e32 v1, v1, v4, vcc
	v_sub_u32_e32 v4, v3, v2
	v_cndmask_b32_e32 v3, v3, v4, vcc
	v_add_u32_e32 v4, 1, v1
	v_cmp_ge_u32_e32 vcc, v3, v2
	v_add_u32_e32 v3, 1, v5
	s_nop 0
	v_cndmask_b32_e32 v1, v1, v4, vcc
	v_mul_lo_u32 v4, v2, v1
	v_add_u32_e32 v2, v4, v2
	v_cmp_ne_u32_e32 vcc, v3, v2
	s_and_saveexec_b64 s[6:7], vcc
	s_xor_b64 s[6:7], exec, s[6:7]
	s_cbranch_execz .LBB0_759
	s_cmp_lg_u32 s101, 0
	s_cselect_b32 s98, 26, 28
	s_cselect_b32 s99, 27, 29
	s_nop 3
	v_readlane_b32 s8, v254, s98
	v_readlane_b32 s9, v254, s99
	s_waitcnt lgkmcnt(0)
	s_nop 3
	global_load_dword v0, v181, s[8:9] sc1
	s_waitcnt vmcnt(0)
	s_cmp_lg_u32 s101, 0
	s_cbranch_scc0 .Lpc_8
	v_cmp_ge_u32_e32 vcc, v0, v2
	s_nop 1
	v_addc_co_u32_e32 v0, vcc, 0, v1, vcc
.Lpc_8:
	v_cmp_eq_u32_e32 vcc, v0, v1
	s_and_saveexec_b64 s[8:9], vcc
	s_cbranch_execz .LBB0_758
	s_mov_b32 s4, 1
	s_mov_b64 s[10:11], 0
	s_branch .LBB0_749

.LBB0_753:
	s_cmp_lg_u32 s101, 0
	s_cselect_b32 s98, 26, 28
	s_cselect_b32 s99, 27, 29
	s_nop 3
	v_readlane_b32 s16, v254, s98
	v_readlane_b32 s17, v254, s99
	s_add_i32 s4, s4, 1
	s_mov_b64 s[20:21], -1
	s_nop 2
	global_load_dword v0, v181, s[16:17] sc1
	s_waitcnt vmcnt(0)
	s_cmp_lg_u32 s101, 0
	s_cbranch_scc0 .Lpc_9
	v_cmp_ge_u32_e32 vcc, v0, v2
	s_nop 1
	v_addc_co_u32_e32 v0, vcc, 0, v1, vcc
.Lpc_9:
	v_cmp_ne_u32_e32 vcc, v0, v1
	s_orn2_b64 s[16:17], vcc, exec
	s_branch .LBB0_748

.LBB0_909:
	s_cmp_lg_u32 s101, 0
	s_cselect_b32 s98, 26, 28
	s_cselect_b32 s99, 27, 29
	s_nop 3
	v_readlane_b32 s16, v254, s98
	v_readlane_b32 s17, v254, s99
	s_add_i32 s4, s4, 1
	s_mov_b64 s[18:19], -1
	s_nop 2
	global_load_dword v0, v181, s[16:17] sc1
	s_waitcnt vmcnt(0)
	s_cmp_lg_u32 s101, 0
	s_cbranch_scc0 .Lpc_11
	v_cmp_ge_u32_e32 vcc, v0, v2
	s_nop 1
	v_addc_co_u32_e32 v0, vcc, 0, v1, vcc
